# v72 + prologue adaLN k-loop: 16 weight loads per unrolled iteration issued up front (were load->vmcnt(0) serialized)
# baseline (speedup 1.0000x reference)
.LBB0_644:
	global_load_dword v80, v[12:13], off nt
	v_add_u32_e32 v96, 34, v0
	v_mad_i64_i32 v[98:99], s[0:1], v96, s33, v[10:11]
	global_load_dword v81, v[98:99], off nt
	v_add_u32_e32 v96, 36, v0
	v_mad_i64_i32 v[98:99], s[0:1], v96, s33, v[10:11]
	global_load_dword v82, v[98:99], off nt
	v_add_u32_e32 v96, 38, v0
	v_mad_i64_i32 v[98:99], s[0:1], v96, s33, v[10:11]
	global_load_dword v83, v[98:99], off nt
	v_add_u32_e32 v96, 40, v0
	v_mad_i64_i32 v[98:99], s[0:1], v96, s33, v[10:11]
	global_load_dword v84, v[98:99], off nt
	v_add_u32_e32 v96, 42, v0
	v_mad_i64_i32 v[98:99], s[0:1], v96, s33, v[10:11]
	global_load_dword v85, v[98:99], off nt
	v_add_u32_e32 v96, 44, v0
	v_mad_i64_i32 v[98:99], s[0:1], v96, s33, v[10:11]
	global_load_dword v86, v[98:99], off nt
	v_add_u32_e32 v96, 46, v0
	v_mad_i64_i32 v[98:99], s[0:1], v96, s33, v[10:11]
	global_load_dword v87, v[98:99], off nt
	v_add_u32_e32 v96, 48, v0
	v_mad_i64_i32 v[98:99], s[0:1], v96, s33, v[10:11]
	global_load_dword v88, v[98:99], off nt
	v_add_u32_e32 v96, 50, v0
	v_mad_i64_i32 v[98:99], s[0:1], v96, s33, v[10:11]
	global_load_dword v89, v[98:99], off nt
	v_add_u32_e32 v96, 52, v0
	v_mad_i64_i32 v[98:99], s[0:1], v96, s33, v[10:11]
	global_load_dword v90, v[98:99], off nt
	v_add_u32_e32 v96, 54, v0
	v_mad_i64_i32 v[98:99], s[0:1], v96, s33, v[10:11]
	global_load_dword v91, v[98:99], off nt
	v_add_u32_e32 v96, 56, v0
	v_mad_i64_i32 v[98:99], s[0:1], v96, s33, v[10:11]
	global_load_dword v92, v[98:99], off nt
	v_add_u32_e32 v96, 58, v0
	v_mad_i64_i32 v[98:99], s[0:1], v96, s33, v[10:11]
	global_load_dword v93, v[98:99], off nt
	v_add_u32_e32 v96, 60, v0
	v_mad_i64_i32 v[98:99], s[0:1], v96, s33, v[10:11]
	global_load_dword v94, v[98:99], off nt
	v_add_u32_e32 v96, 62, v0
	v_mad_i64_i32 v[98:99], s[0:1], v96, s33, v[10:11]
	global_load_dword v95, v[98:99], off nt
	s_waitcnt vmcnt(15)
	v_mov_b32_e32 v36, v80
	v_add_u32_e32 v34, 0x1000, v33
	ds_read2_b32 v[38:39], v34 offset1:2
	ds_read2_b32 v[40:41], v33 offset1:2
	ds_read2_b32 v[26:27], v33 offset0:4 offset1:6
	ds_read2_b32 v[24:25], v33 offset0:8 offset1:10
	ds_read2_b32 v[22:23], v33 offset0:12 offset1:14
	s_waitcnt lgkmcnt(4)
	v_mov_b32_e32 v43, v38
	s_waitcnt lgkmcnt(3)
	v_mov_b32_e32 v42, v40
	v_mov_b32_e32 v38, v41
	v_pk_fma_f32 v[42:43], v[36:37], v[42:43], v[20:21] op_sel_hi:[0,1,1]
	v_add_u32_e32 v20, 0x2000, v33
	v_add_u32_e32 v21, 0x3000, v33
	ds_read2_b32 v[44:45], v20 offset1:2
	ds_read2_b32 v[46:47], v21 offset1:2
	s_waitcnt lgkmcnt(1)
	v_mov_b32_e32 v48, v44
	s_waitcnt lgkmcnt(0)
	v_mov_b32_e32 v49, v46
	v_pk_fma_f32 v[48:49], v[36:37], v[48:49], v[18:19] op_sel_hi:[0,1,1]
	v_add_u32_e32 v18, 0x4000, v33
	v_add_u32_e32 v19, 0x5000, v33
	ds_read2_b32 v[50:51], v18 offset1:2
	ds_read2_b32 v[52:53], v19 offset1:2
	v_mov_b32_e32 v46, v45
	s_waitcnt lgkmcnt(1)
	v_mov_b32_e32 v54, v50
	s_waitcnt lgkmcnt(0)
	v_mov_b32_e32 v55, v52
	v_pk_fma_f32 v[54:55], v[36:37], v[54:55], v[16:17] op_sel_hi:[0,1,1]
	v_add_u32_e32 v16, 0x6000, v33
	v_add_u32_e32 v17, 0x7000, v33
	ds_read2_b32 v[56:57], v16 offset1:2
	ds_read2_b32 v[58:59], v17 offset1:2
	v_mov_b32_e32 v52, v51
	s_waitcnt lgkmcnt(1)
	v_mov_b32_e32 v60, v56
	s_waitcnt lgkmcnt(0)
	v_mov_b32_e32 v61, v58
	v_pk_fma_f32 v[60:61], v[36:37], v[60:61], v[14:15] op_sel_hi:[0,1,1]
	v_add_u32_e32 v14, 0x8000, v33
	ds_read2_b32 v[62:63], v14 offset1:2
	v_add_u32_e32 v15, 34, v0
	v_mov_b32_e32 v58, v57
	s_waitcnt lgkmcnt(0)
	v_fmac_f32_e32 v32, v36, v62
	v_mad_i64_i32 v[36:37], s[0:1], v15, s33, v[10:11]
	s_waitcnt vmcnt(14)
	v_mov_b32_e32 v36, v81
	v_add_u32_e32 v15, 36, v0
	v_pk_fma_f32 v[38:39], v[36:37], v[38:39], v[42:43] op_sel_hi:[0,1,1]
	v_pk_fma_f32 v[40:41], v[36:37], v[46:47], v[48:49] op_sel_hi:[0,1,1]
	v_pk_fma_f32 v[42:43], v[36:37], v[52:53], v[54:55] op_sel_hi:[0,1,1]
	v_pk_fma_f32 v[44:45], v[36:37], v[58:59], v[60:61] op_sel_hi:[0,1,1]
	v_fmac_f32_e32 v32, v36, v63
	v_mad_i64_i32 v[36:37], s[0:1], v15, s33, v[10:11]
	s_waitcnt vmcnt(13)
	v_mov_b32_e32 v36, v82
	ds_read2_b32 v[46:47], v34 offset0:4 offset1:6
	v_mov_b32_e32 v48, v26
	v_add_u32_e32 v15, 38, v0
	s_waitcnt lgkmcnt(0)
	v_mov_b32_e32 v49, v46
	v_mov_b32_e32 v46, v27
	v_pk_fma_f32 v[38:39], v[36:37], v[48:49], v[38:39] op_sel_hi:[0,1,1]
	ds_read2_b32 v[48:49], v20 offset0:4 offset1:6
	ds_read2_b32 v[50:51], v21 offset0:4 offset1:6
	s_waitcnt lgkmcnt(1)
	v_mov_b32_e32 v52, v48
	s_waitcnt lgkmcnt(0)
	v_mov_b32_e32 v53, v50
	v_pk_fma_f32 v[40:41], v[36:37], v[52:53], v[40:41] op_sel_hi:[0,1,1]
	ds_read2_b32 v[52:53], v18 offset0:4 offset1:6
	ds_read2_b32 v[54:55], v19 offset0:4 offset1:6
	v_mov_b32_e32 v50, v49
	s_waitcnt lgkmcnt(1)
	v_mov_b32_e32 v56, v52
	s_waitcnt lgkmcnt(0)
	v_mov_b32_e32 v57, v54
	v_pk_fma_f32 v[42:43], v[36:37], v[56:57], v[42:43] op_sel_hi:[0,1,1]
	ds_read2_b32 v[56:57], v16 offset0:4 offset1:6
	ds_read2_b32 v[58:59], v17 offset0:4 offset1:6
	v_mov_b32_e32 v54, v53
	s_waitcnt lgkmcnt(1)
	v_mov_b32_e32 v60, v56
	s_waitcnt lgkmcnt(0)
	v_mov_b32_e32 v61, v58
	v_pk_fma_f32 v[44:45], v[36:37], v[60:61], v[44:45] op_sel_hi:[0,1,1]
	ds_read2_b32 v[60:61], v14 offset0:4 offset1:6
	v_mov_b32_e32 v58, v57
	s_waitcnt lgkmcnt(0)
	v_fmac_f32_e32 v32, v36, v60
	v_mad_i64_i32 v[36:37], s[0:1], v15, s33, v[10:11]
	s_waitcnt vmcnt(12)
	v_mov_b32_e32 v26, v83
	v_add_u32_e32 v15, 40, v0
	v_pk_fma_f32 v[36:37], v[26:27], v[46:47], v[38:39] op_sel_hi:[0,1,1]
	v_pk_fma_f32 v[38:39], v[26:27], v[50:51], v[40:41] op_sel_hi:[0,1,1]
	v_pk_fma_f32 v[40:41], v[26:27], v[54:55], v[42:43] op_sel_hi:[0,1,1]
	v_pk_fma_f32 v[42:43], v[26:27], v[58:59], v[44:45] op_sel_hi:[0,1,1]
	v_fmac_f32_e32 v32, v26, v61
	v_mad_i64_i32 v[26:27], s[0:1], v15, s33, v[10:11]
	s_waitcnt vmcnt(11)
	v_mov_b32_e32 v26, v84
	ds_read2_b32 v[44:45], v34 offset0:8 offset1:10
	v_mov_b32_e32 v46, v24
	v_add_u32_e32 v15, 42, v0
	s_waitcnt lgkmcnt(0)
	v_mov_b32_e32 v47, v44
	v_mov_b32_e32 v44, v25
	v_pk_fma_f32 v[36:37], v[26:27], v[46:47], v[36:37] op_sel_hi:[0,1,1]
	ds_read2_b32 v[46:47], v20 offset0:8 offset1:10
	ds_read2_b32 v[48:49], v21 offset0:8 offset1:10
	s_waitcnt lgkmcnt(1)
	v_mov_b32_e32 v50, v46
	s_waitcnt lgkmcnt(0)
	v_mov_b32_e32 v51, v48
	v_pk_fma_f32 v[38:39], v[26:27], v[50:51], v[38:39] op_sel_hi:[0,1,1]
	ds_read2_b32 v[50:51], v18 offset0:8 offset1:10
	ds_read2_b32 v[52:53], v19 offset0:8 offset1:10
	v_mov_b32_e32 v48, v47
	s_waitcnt lgkmcnt(1)
	v_mov_b32_e32 v54, v50
	s_waitcnt lgkmcnt(0)
	v_mov_b32_e32 v55, v52
	v_pk_fma_f32 v[40:41], v[26:27], v[54:55], v[40:41] op_sel_hi:[0,1,1]
	ds_read2_b32 v[54:55], v16 offset0:8 offset1:10
	ds_read2_b32 v[56:57], v17 offset0:8 offset1:10
	v_mov_b32_e32 v52, v51
	s_waitcnt lgkmcnt(1)
	v_mov_b32_e32 v58, v54
	s_waitcnt lgkmcnt(0)
	v_mov_b32_e32 v59, v56
	v_pk_fma_f32 v[42:43], v[26:27], v[58:59], v[42:43] op_sel_hi:[0,1,1]
	ds_read2_b32 v[58:59], v14 offset0:8 offset1:10
	v_mov_b32_e32 v56, v55
	s_waitcnt lgkmcnt(0)
	v_fmac_f32_e32 v32, v26, v58
	v_mad_i64_i32 v[26:27], s[0:1], v15, s33, v[10:11]
	s_waitcnt vmcnt(10)
	v_mov_b32_e32 v24, v85
	v_add_u32_e32 v15, 44, v0
	v_pk_fma_f32 v[26:27], v[24:25], v[44:45], v[36:37] op_sel_hi:[0,1,1]
	v_pk_fma_f32 v[36:37], v[24:25], v[48:49], v[38:39] op_sel_hi:[0,1,1]
	v_pk_fma_f32 v[38:39], v[24:25], v[52:53], v[40:41] op_sel_hi:[0,1,1]
	v_pk_fma_f32 v[40:41], v[24:25], v[56:57], v[42:43] op_sel_hi:[0,1,1]
	v_fmac_f32_e32 v32, v24, v59
	v_mad_i64_i32 v[24:25], s[0:1], v15, s33, v[10:11]
	s_waitcnt vmcnt(9)
	v_mov_b32_e32 v24, v86
	ds_read2_b32 v[42:43], v34 offset0:12 offset1:14
	v_mov_b32_e32 v44, v22
	v_add_u32_e32 v15, 46, v0
	s_waitcnt lgkmcnt(0)
	v_mov_b32_e32 v45, v42
	v_mov_b32_e32 v42, v23
	v_pk_fma_f32 v[26:27], v[24:25], v[44:45], v[26:27] op_sel_hi:[0,1,1]
	ds_read2_b32 v[44:45], v20 offset0:12 offset1:14
	ds_read2_b32 v[46:47], v21 offset0:12 offset1:14
	s_waitcnt lgkmcnt(1)
	v_mov_b32_e32 v48, v44
	s_waitcnt lgkmcnt(0)
	v_mov_b32_e32 v49, v46
	v_pk_fma_f32 v[36:37], v[24:25], v[48:49], v[36:37] op_sel_hi:[0,1,1]
	ds_read2_b32 v[48:49], v18 offset0:12 offset1:14
	ds_read2_b32 v[50:51], v19 offset0:12 offset1:14
	v_mov_b32_e32 v46, v45
	s_waitcnt lgkmcnt(1)
	v_mov_b32_e32 v52, v48
	s_waitcnt lgkmcnt(0)
	v_mov_b32_e32 v53, v50
	v_pk_fma_f32 v[38:39], v[24:25], v[52:53], v[38:39] op_sel_hi:[0,1,1]
	ds_read2_b32 v[52:53], v16 offset0:12 offset1:14
	ds_read2_b32 v[54:55], v17 offset0:12 offset1:14
	v_mov_b32_e32 v50, v49
	s_waitcnt lgkmcnt(1)
	v_mov_b32_e32 v56, v52
	s_waitcnt lgkmcnt(0)
	v_mov_b32_e32 v57, v54
	v_pk_fma_f32 v[40:41], v[24:25], v[56:57], v[40:41] op_sel_hi:[0,1,1]
	ds_read2_b32 v[56:57], v14 offset0:12 offset1:14
	v_mov_b32_e32 v54, v53
	s_waitcnt lgkmcnt(0)
	v_fmac_f32_e32 v32, v24, v56
	v_mad_i64_i32 v[24:25], s[0:1], v15, s33, v[10:11]
	s_waitcnt vmcnt(8)
	v_mov_b32_e32 v22, v87
	v_add_u32_e32 v15, 48, v0
	v_pk_fma_f32 v[24:25], v[22:23], v[42:43], v[26:27] op_sel_hi:[0,1,1]
	v_pk_fma_f32 v[26:27], v[22:23], v[46:47], v[36:37] op_sel_hi:[0,1,1]
	v_pk_fma_f32 v[36:37], v[22:23], v[50:51], v[38:39] op_sel_hi:[0,1,1]
	v_pk_fma_f32 v[38:39], v[22:23], v[54:55], v[40:41] op_sel_hi:[0,1,1]
	v_fmac_f32_e32 v32, v22, v57
	v_mad_i64_i32 v[22:23], s[0:1], v15, s33, v[10:11]
	s_waitcnt vmcnt(7)
	v_mov_b32_e32 v22, v88
	ds_read2_b32 v[40:41], v33 offset0:16 offset1:18
	ds_read2_b32 v[42:43], v34 offset0:16 offset1:18
	v_add_u32_e32 v15, 50, v0
	s_waitcnt lgkmcnt(1)
	v_mov_b32_e32 v44, v40
	s_waitcnt lgkmcnt(0)
	v_mov_b32_e32 v45, v42
	v_mov_b32_e32 v42, v41
	v_pk_fma_f32 v[24:25], v[22:23], v[44:45], v[24:25] op_sel_hi:[0,1,1]
	ds_read2_b32 v[44:45], v20 offset0:16 offset1:18
	ds_read2_b32 v[46:47], v21 offset0:16 offset1:18
	s_waitcnt lgkmcnt(1)
	v_mov_b32_e32 v48, v44
	s_waitcnt lgkmcnt(0)
	v_mov_b32_e32 v49, v46
	v_pk_fma_f32 v[26:27], v[22:23], v[48:49], v[26:27] op_sel_hi:[0,1,1]
	ds_read2_b32 v[48:49], v18 offset0:16 offset1:18
	ds_read2_b32 v[50:51], v19 offset0:16 offset1:18
	v_mov_b32_e32 v46, v45
	s_waitcnt lgkmcnt(1)
	v_mov_b32_e32 v52, v48
	s_waitcnt lgkmcnt(0)
	v_mov_b32_e32 v53, v50
	v_pk_fma_f32 v[36:37], v[22:23], v[52:53], v[36:37] op_sel_hi:[0,1,1]
	ds_read2_b32 v[52:53], v16 offset0:16 offset1:18
	ds_read2_b32 v[54:55], v17 offset0:16 offset1:18
	v_mov_b32_e32 v50, v49
	s_waitcnt lgkmcnt(1)
	v_mov_b32_e32 v56, v52
	s_waitcnt lgkmcnt(0)
	v_mov_b32_e32 v57, v54
	v_pk_fma_f32 v[38:39], v[22:23], v[56:57], v[38:39] op_sel_hi:[0,1,1]
	ds_read2_b32 v[56:57], v14 offset0:16 offset1:18
	v_mov_b32_e32 v54, v53
	s_waitcnt lgkmcnt(0)
	v_fmac_f32_e32 v32, v22, v56
	v_mad_i64_i32 v[22:23], s[0:1], v15, s33, v[10:11]
	s_waitcnt vmcnt(6)
	v_mov_b32_e32 v22, v89
	v_add_u32_e32 v15, 52, v0
	v_pk_fma_f32 v[24:25], v[22:23], v[42:43], v[24:25] op_sel_hi:[0,1,1]
	v_pk_fma_f32 v[26:27], v[22:23], v[46:47], v[26:27] op_sel_hi:[0,1,1]
	v_pk_fma_f32 v[36:37], v[22:23], v[50:51], v[36:37] op_sel_hi:[0,1,1]
	v_pk_fma_f32 v[38:39], v[22:23], v[54:55], v[38:39] op_sel_hi:[0,1,1]
	v_fmac_f32_e32 v32, v22, v57
	v_mad_i64_i32 v[22:23], s[0:1], v15, s33, v[10:11]
	s_waitcnt vmcnt(5)
	v_mov_b32_e32 v22, v90
	ds_read2_b32 v[40:41], v33 offset0:20 offset1:22
	ds_read2_b32 v[42:43], v34 offset0:20 offset1:22
	v_add_u32_e32 v15, 54, v0
	s_waitcnt lgkmcnt(1)
	v_mov_b32_e32 v44, v40
	s_waitcnt lgkmcnt(0)
	v_mov_b32_e32 v45, v42
	v_mov_b32_e32 v42, v41
	v_pk_fma_f32 v[24:25], v[22:23], v[44:45], v[24:25] op_sel_hi:[0,1,1]
	ds_read2_b32 v[44:45], v20 offset0:20 offset1:22
	ds_read2_b32 v[46:47], v21 offset0:20 offset1:22
	s_waitcnt lgkmcnt(1)
	v_mov_b32_e32 v48, v44
	s_waitcnt lgkmcnt(0)
	v_mov_b32_e32 v49, v46
	v_pk_fma_f32 v[26:27], v[22:23], v[48:49], v[26:27] op_sel_hi:[0,1,1]
	ds_read2_b32 v[48:49], v18 offset0:20 offset1:22
	ds_read2_b32 v[50:51], v19 offset0:20 offset1:22
	v_mov_b32_e32 v46, v45
	s_waitcnt lgkmcnt(1)
	v_mov_b32_e32 v52, v48
	s_waitcnt lgkmcnt(0)
	v_mov_b32_e32 v53, v50
	v_pk_fma_f32 v[36:37], v[22:23], v[52:53], v[36:37] op_sel_hi:[0,1,1]
	ds_read2_b32 v[52:53], v16 offset0:20 offset1:22
	ds_read2_b32 v[54:55], v17 offset0:20 offset1:22
	v_mov_b32_e32 v50, v49
	s_waitcnt lgkmcnt(1)
	v_mov_b32_e32 v56, v52
	s_waitcnt lgkmcnt(0)
	v_mov_b32_e32 v57, v54
	v_pk_fma_f32 v[38:39], v[22:23], v[56:57], v[38:39] op_sel_hi:[0,1,1]
	ds_read2_b32 v[56:57], v14 offset0:20 offset1:22
	v_mov_b32_e32 v54, v53
	s_waitcnt lgkmcnt(0)
	v_fmac_f32_e32 v32, v22, v56
	v_mad_i64_i32 v[22:23], s[0:1], v15, s33, v[10:11]
	s_waitcnt vmcnt(4)
	v_mov_b32_e32 v22, v91
	v_add_u32_e32 v15, 56, v0
	v_pk_fma_f32 v[24:25], v[22:23], v[42:43], v[24:25] op_sel_hi:[0,1,1]
	v_pk_fma_f32 v[26:27], v[22:23], v[46:47], v[26:27] op_sel_hi:[0,1,1]
	v_pk_fma_f32 v[36:37], v[22:23], v[50:51], v[36:37] op_sel_hi:[0,1,1]
	v_pk_fma_f32 v[38:39], v[22:23], v[54:55], v[38:39] op_sel_hi:[0,1,1]
	v_fmac_f32_e32 v32, v22, v57
	v_mad_i64_i32 v[22:23], s[0:1], v15, s33, v[10:11]
	s_waitcnt vmcnt(3)
	v_mov_b32_e32 v22, v92
	ds_read2_b32 v[40:41], v33 offset0:24 offset1:26
	ds_read2_b32 v[42:43], v34 offset0:24 offset1:26
	v_add_u32_e32 v15, 58, v0
	s_waitcnt lgkmcnt(1)
	v_mov_b32_e32 v44, v40
	s_waitcnt lgkmcnt(0)
	v_mov_b32_e32 v45, v42
	v_mov_b32_e32 v42, v41
	v_pk_fma_f32 v[24:25], v[22:23], v[44:45], v[24:25] op_sel_hi:[0,1,1]
	ds_read2_b32 v[44:45], v20 offset0:24 offset1:26
	ds_read2_b32 v[46:47], v21 offset0:24 offset1:26
	s_waitcnt lgkmcnt(1)
	v_mov_b32_e32 v48, v44
	s_waitcnt lgkmcnt(0)
	v_mov_b32_e32 v49, v46
	v_pk_fma_f32 v[26:27], v[22:23], v[48:49], v[26:27] op_sel_hi:[0,1,1]
	ds_read2_b32 v[48:49], v18 offset0:24 offset1:26
	ds_read2_b32 v[50:51], v19 offset0:24 offset1:26
	v_mov_b32_e32 v46, v45
	s_waitcnt lgkmcnt(1)
	v_mov_b32_e32 v52, v48
	s_waitcnt lgkmcnt(0)
	v_mov_b32_e32 v53, v50
	v_pk_fma_f32 v[36:37], v[22:23], v[52:53], v[36:37] op_sel_hi:[0,1,1]
	ds_read2_b32 v[52:53], v16 offset0:24 offset1:26
	ds_read2_b32 v[54:55], v17 offset0:24 offset1:26
	v_mov_b32_e32 v50, v49
	s_waitcnt lgkmcnt(1)
	v_mov_b32_e32 v56, v52
	s_waitcnt lgkmcnt(0)
	v_mov_b32_e32 v57, v54
	v_pk_fma_f32 v[38:39], v[22:23], v[56:57], v[38:39] op_sel_hi:[0,1,1]
	ds_read2_b32 v[56:57], v14 offset0:24 offset1:26
	v_mov_b32_e32 v54, v53
	s_waitcnt lgkmcnt(0)
	v_fmac_f32_e32 v32, v22, v56
	v_mad_i64_i32 v[22:23], s[0:1], v15, s33, v[10:11]
	s_waitcnt vmcnt(2)
	v_mov_b32_e32 v22, v93
	v_add_u32_e32 v15, 60, v0
	v_pk_fma_f32 v[24:25], v[22:23], v[42:43], v[24:25] op_sel_hi:[0,1,1]
	v_pk_fma_f32 v[26:27], v[22:23], v[46:47], v[26:27] op_sel_hi:[0,1,1]
	v_pk_fma_f32 v[36:37], v[22:23], v[50:51], v[36:37] op_sel_hi:[0,1,1]
	v_pk_fma_f32 v[38:39], v[22:23], v[54:55], v[38:39] op_sel_hi:[0,1,1]
	v_fmac_f32_e32 v32, v22, v57
	v_mad_i64_i32 v[22:23], s[0:1], v15, s33, v[10:11]
	s_waitcnt vmcnt(1)
	v_mov_b32_e32 v22, v94
	ds_read2_b32 v[40:41], v33 offset0:28 offset1:30
	ds_read2_b32 v[34:35], v34 offset0:28 offset1:30
	v_add_u32_e32 v33, 0x80, v33
	s_waitcnt lgkmcnt(1)
	v_mov_b32_e32 v42, v40
	s_waitcnt lgkmcnt(0)
	v_mov_b32_e32 v43, v34
	v_mov_b32_e32 v34, v41
	v_pk_fma_f32 v[24:25], v[22:23], v[42:43], v[24:25] op_sel_hi:[0,1,1]
	ds_read2_b32 v[42:43], v20 offset0:28 offset1:30
	ds_read2_b32 v[44:45], v21 offset0:28 offset1:30
	ds_read2_b32 v[46:47], v18 offset0:28 offset1:30
	ds_read2_b32 v[48:49], v19 offset0:28 offset1:30
	ds_read2_b32 v[50:51], v16 offset0:28 offset1:30
	ds_read2_b32 v[52:53], v17 offset0:28 offset1:30
	ds_read2_b32 v[54:55], v14 offset0:28 offset1:30
	v_add_u32_e32 v14, 62, v0
	s_waitcnt lgkmcnt(6)
	v_mov_b32_e32 v20, v42
	s_waitcnt lgkmcnt(5)
	v_mov_b32_e32 v21, v44
	s_waitcnt lgkmcnt(4)
	v_mov_b32_e32 v18, v46
	s_waitcnt lgkmcnt(3)
	v_mov_b32_e32 v19, v48
	s_waitcnt lgkmcnt(2)
	v_mov_b32_e32 v16, v50
	s_waitcnt lgkmcnt(1)
	v_mov_b32_e32 v17, v52
	v_mad_i64_i32 v[14:15], s[0:1], v14, s33, v[10:11]
	v_pk_fma_f32 v[26:27], v[22:23], v[20:21], v[26:27] op_sel_hi:[0,1,1]
	v_pk_fma_f32 v[36:37], v[22:23], v[18:19], v[36:37] op_sel_hi:[0,1,1]
	v_pk_fma_f32 v[38:39], v[22:23], v[16:17], v[38:39] op_sel_hi:[0,1,1]
	s_waitcnt lgkmcnt(0)
	v_fmac_f32_e32 v32, v22, v54
	s_waitcnt vmcnt(0)
	v_mov_b32_e32 v22, v95
	v_add_u32_e32 v0, 32, v0
	s_mov_b64 s[0:1], 0xc0000
	v_mov_b32_e32 v44, v43
	v_mov_b32_e32 v48, v47
	v_mov_b32_e32 v52, v51
	v_lshl_add_u64 v[12:13], v[12:13], 0, s[0:1]
	v_cmp_le_i32_e64 s[0:1], s4, v0
	s_or_b64 s[24:25], s[0:1], s[24:25]
	v_pk_fma_f32 v[20:21], v[22:23], v[34:35], v[24:25] op_sel_hi:[0,1,1]
	v_pk_fma_f32 v[18:19], v[22:23], v[44:45], v[26:27] op_sel_hi:[0,1,1]
	v_pk_fma_f32 v[16:17], v[22:23], v[48:49], v[36:37] op_sel_hi:[0,1,1]
	v_pk_fma_f32 v[14:15], v[22:23], v[52:53], v[38:39] op_sel_hi:[0,1,1]
	v_fmac_f32_e32 v32, v22, v55
	s_andn2_b64 exec, exec, s[24:25]
	s_cbranch_execnz .LBB0_644
	s_or_b64 exec, exec, s[24:25]
